# P2 short-conv loop: rows t, t-1, t-2 and gate loaded together (one wait per item instead of three); loop-invariant conv weights loaded once
# speedup vs baseline: 1.0055x; 1.0055x over previous
.LBB0_403:
	v_readlane_b32 s84, v248, 32
	v_readlane_b32 s82, v248, 37
	s_cmp_gt_i32 s84, 63
	v_readlane_b32 s66, v248, 30
	v_readlane_b32 s83, v248, 38
	v_readlane_b32 s67, v248, 31
	s_cbranch_scc0 .LBB0_440
	s_lshl_b32 s0, s84, 3
	v_readlane_b32 s1, v248, 0
	s_add_i32 s0, s0, s1
	s_lshl_b32 s0, s0, 6
	s_addk_i32 s0, 0x8000
	s_lshl_b32 s19, s95, 9
	v_or_b32_e32 v26, s0, v206
	s_mov_b32 s0, 0x240000
	s_mov_b64 s[2:3], s[96:97]
	s_mov_b64 s[6:7], s[96:97]
	s_add_i32 s18, s19, 0xffff8000
	v_cmp_gt_i32_e32 vcc, s0, v26
	s_and_saveexec_b64 s[0:1], vcc
	s_cbranch_execz .LBB0_427
	s_load_dwordx2 s[4:5], s[2:3], 0x20
	s_nop 0
	s_load_dwordx2 s[6:7], s[6:7], 0x90
	s_lshl_b32 s20, s95, 12
	v_lshlrev_b32_e32 v1, 3, v26
	s_add_i32 s20, s20, 0xfffc0000
	s_mov_b64 s[8:9], 0
	v_mov_b32_e32 v29, 0
	s_movk_i32 s21, 0x1fff
	s_movk_i32 s22, 0x1800
	s_mov_b32 s23, 0xffff0000
	s_movk_i32 s24, 0xf00
	s_movk_i32 s25, 0x2000
	s_mov_b64 s[10:11], 0x2000
	s_mov_b64 s[12:13], 0x4000
	s_movk_i32 s26, 0x4000
	s_movk_i32 s27, 0x7fff
	s_mov_b32 s28, 0x23ffff
	v_mov_b32_e32 v27, 0x15000
	v_mov_b32_e32 v38, 0xffffe800
	v_mov_b32_e32 v39, 0x16800
	v_mov_b32_e32 v40, 0x2000
	v_mov_b32_e32 v41, v26
	s_waitcnt lgkmcnt(0)
	v_and_b32_e32 v72, 0x7f8, v1
	v_lshlrev_b32_e32 v72, 2, v72
	v_add_u32_e32 v73, 0x2000, v72
	v_add_u32_e32 v74, 0x4000, v72
	global_load_dwordx4 v[76:79], v72, s[6:7] offset:16
	global_load_dwordx4 v[80:83], v72, s[6:7]
	global_load_dwordx4 v[84:87], v73, s[6:7]
	global_load_dwordx4 v[88:91], v74, s[6:7]
	global_load_dwordx4 v[92:95], v73, s[6:7] offset:16
	global_load_dwordx4 v[96:99], v74, s[6:7] offset:16
	s_waitcnt vmcnt(0)
	s_branch .LBB0_407
.LBB0_406:
	s_or_b64 exec, exec, s[2:3]
	v_mov_b32_e32 v33, v29
	s_waitcnt lgkmcnt(0)
	v_lshl_add_u64 v[18:19], s[6:7], 0, v[32:33]
	v_add_co_u32_e32 v22, vcc, s25, v18
	v_mov_b32_e32 v42, v76
	v_mov_b32_e32 v43, v77
	v_mov_b32_e32 v44, v78
	v_mov_b32_e32 v45, v79
	v_mov_b32_e32 v46, v80
	v_mov_b32_e32 v47, v81
	v_mov_b32_e32 v48, v82
	v_mov_b32_e32 v49, v83
	v_addc_co_u32_e32 v23, vcc, 0, v19, vcc
	v_mov_b32_e32 v50, v84
	v_mov_b32_e32 v51, v85
	v_mov_b32_e32 v52, v86
	v_mov_b32_e32 v53, v87
	v_add_co_u32_e32 v22, vcc, s26, v18
	s_waitcnt vmcnt(0)
	v_lshlrev_b32_e32 v33, 16, v9
	v_addc_co_u32_e32 v23, vcc, 0, v19, vcc
	v_mov_b32_e32 v54, v88
	v_mov_b32_e32 v55, v89
	v_mov_b32_e32 v56, v90
	v_mov_b32_e32 v57, v91
	v_lshl_add_u64 v[22:23], v[18:19], 0, s[10:11]
	v_mov_b32_e32 v58, v92
	v_mov_b32_e32 v59, v93
	v_mov_b32_e32 v60, v94
	v_mov_b32_e32 v61, v95
	v_lshl_add_u64 v[18:19], v[18:19], 0, s[12:13]
	v_mov_b32_e32 v62, v96
	v_mov_b32_e32 v63, v97
	v_mov_b32_e32 v64, v98
	v_mov_b32_e32 v65, v99
	v_lshlrev_b32_e32 v23, 16, v7
	v_lshlrev_b32_e32 v22, 16, v6
	v_and_b32_e32 v7, 0xffff0000, v7
	v_and_b32_e32 v6, 0xffff0000, v6
	v_lshlrev_b32_e32 v32, 16, v8
	v_lshlrev_b64 v[18:19], 11, v[30:31]
	v_lshlrev_b32_e32 v31, 16, v3
	v_lshlrev_b32_e32 v30, 16, v2
	v_and_b32_e32 v3, 0xffff0000, v3
	v_and_b32_e32 v2, 0xffff0000, v2
	v_and_b32_e32 v9, 0xffff0000, v9
	v_and_b32_e32 v8, 0xffff0000, v8
	v_lshlrev_b32_e32 v67, 16, v5
	v_lshlrev_b32_e32 v66, 16, v4
	v_and_b32_e32 v5, 0xffff0000, v5
	v_and_b32_e32 v4, 0xffff0000, v4
	v_add_u32_e32 v41, s18, v41
	v_cmp_lt_i32_e32 vcc, s28, v41
	s_or_b64 s[8:9], vcc, s[8:9]
	v_add_u32_e32 v1, s20, v1
	v_mov_b32_e32 v68, v46
	v_mov_b32_e32 v69, v48
	v_mov_b32_e32 v48, v47
	v_mov_b32_e32 v46, v42
	v_mov_b32_e32 v47, v44
	v_mov_b32_e32 v44, v43
	v_mov_b32_e32 v42, v50
	v_mov_b32_e32 v43, v52
	v_mov_b32_e32 v52, v51
	v_pk_mul_f32 v[16:17], v[16:17], v[52:53]
	s_waitcnt vmcnt(2)
	v_mov_b32_e32 v70, v54
	s_waitcnt vmcnt(1)
	v_mov_b32_e32 v50, v58
	v_mov_b32_e32 v51, v60
	v_mov_b32_e32 v60, v59
	v_pk_mul_f32 v[34:35], v[34:35], v[50:51]
	v_mov_b32_e32 v71, v56
	v_mov_b32_e32 v56, v55
	s_waitcnt vmcnt(0)
	v_mov_b32_e32 v54, v62
	v_mov_b32_e32 v55, v64
	v_pk_mul_f32 v[10:11], v[10:11], v[42:43]
	v_pk_mul_f32 v[12:13], v[12:13], v[60:61]
	v_pk_fma_f32 v[16:17], v[24:25], v[48:49], v[16:17]
	v_pk_fma_f32 v[14:15], v[14:15], v[46:47], v[34:35]
	v_mov_b32_e32 v64, v63
	v_pk_fma_f32 v[10:11], v[36:37], v[68:69], v[10:11]
	v_pk_fma_f32 v[12:13], v[20:21], v[44:45], v[12:13]
	v_pk_fma_f32 v[6:7], v[56:57], v[6:7], v[16:17]
	v_pk_fma_f32 v[14:15], v[54:55], v[32:33], v[14:15]
	v_pk_fma_f32 v[10:11], v[70:71], v[22:23], v[10:11]
	v_pk_fma_f32 v[8:9], v[64:65], v[8:9], v[12:13]
	v_pk_mul_f32 v[2:3], v[6:7], v[2:3]
	v_pk_mul_f32 v[6:7], v[14:15], v[66:67]
	v_pk_mul_f32 v[10:11], v[10:11], v[30:31]
	v_pk_mul_f32 v[4:5], v[8:9], v[4:5]
	v_bfe_u32 v16, v6, 16, 1
	v_bfe_u32 v17, v7, 16, 1
	v_bfe_u32 v8, v3, 16, 1
	v_bfe_u32 v9, v2, 16, 1
	v_bfe_u32 v12, v5, 16, 1
	v_bfe_u32 v13, v4, 16, 1
	v_bfe_u32 v14, v10, 16, 1
	v_bfe_u32 v15, v11, 16, 1
	v_add3_u32 v7, v7, v17, s27
	v_add3_u32 v6, v6, v16, s27
	v_add3_u32 v2, v2, v9, s27
	v_add3_u32 v3, v3, v8, s27
	v_add3_u32 v4, v4, v13, s27
	v_add3_u32 v5, v5, v12, s27
	v_add3_u32 v8, v11, v15, s27
	v_add3_u32 v9, v10, v14, s27
	v_lshrrev_b32_e32 v6, 16, v6
	v_lshrrev_b32_e32 v7, 16, v7
	v_lshrrev_b32_e32 v9, 16, v9
	v_lshrrev_b32_e32 v8, 16, v8
	v_and_or_b32 v5, v5, s23, v7
	v_and_or_b32 v4, v4, s23, v6
	v_lshl_add_u64 v[6:7], v[18:19], 1, s[70:71]
	v_and_or_b32 v3, v3, s23, v8
	v_and_or_b32 v2, v2, s23, v9
	v_lshl_add_u64 v[6:7], v[6:7], 0, v[28:29]
	global_store_dwordx4 v[6:7], v[2:5], off
	s_andn2_b64 exec, exec, s[8:9]
	s_cbranch_execz .LBB0_427
.LBB0_407:
	v_ashrrev_i32_e32 v30, 8, v41
	v_ashrrev_i32_e32 v31, 31, v30
	v_readlane_b32 s2, v248, 45
	v_lshlrev_b64 v[2:3], 12, v[30:31]
	v_readlane_b32 s3, v248, 46
	v_and_b32_e32 v10, 0x7f8, v1
	v_lshlrev_b32_e32 v28, 1, v10
	v_lshl_add_u64 v[4:5], s[2:3], 0, v[2:3]
	v_readlane_b32 s2, v248, 49
	v_readlane_b32 s3, v248, 50
	v_lshl_add_u64 v[4:5], v[4:5], 0, v[28:29]
	global_load_dwordx4 v[100:103], v[4:5], off offset:-4096
	v_add_co_u32_e32 v104, vcc, 0xffffe000, v4
	s_nop 1
	v_addc_co_u32_e32 v105, vcc, -1, v5, vcc
	global_load_dwordx4 v[106:109], v[104:105], off
	v_cmp_lt_i32_e32 vcc, s21, v30
	v_lshl_add_u64 v[2:3], s[2:3], 0, v[2:3]
	v_lshl_add_u64 v[2:3], v[2:3], 0, v[28:29]
	global_load_dwordx4 v[6:9], v[4:5], off
	s_nop 0
	global_load_dwordx4 v[2:5], v[2:3], off
	v_lshlrev_b32_e32 v32, 2, v10
	s_and_saveexec_b64 s[2:3], vcc
	s_xor_b64 s[2:3], exec, s[2:3]
	s_cbranch_execz .LBB0_409
	v_add_u32_e32 v10, 0xffffe000, v30
	v_lshrrev_b32_e32 v10, 2, v10
	v_and_b32_e32 v12, 0x3ffffffe, v10
	v_or_b32_e32 v10, 1, v10
	v_mov_b32_e32 v11, v29
	v_lshlrev_b64 v[10:11], 13, v[10:11]
	v_bfe_u32 v24, v41, 8, 3
	s_waitcnt lgkmcnt(0)
	v_lshl_add_u64 v[10:11], s[4:5], 0, v[10:11]
	v_mov_b32_e32 v33, v29
	v_lshl_add_u64 v[10:11], v[10:11], 0, v[32:33]
	v_cmp_eq_u32_e32 vcc, 0, v24
	s_nop 1
	v_cndmask_b32_e32 v15, 0, v11, vcc
	v_cndmask_b32_e32 v14, 0, v10, vcc
	v_add_u32_e32 v10, v12, v24
	v_mov_b32_e32 v11, v29
	v_lshlrev_b64 v[10:11], 13, v[10:11]
	v_lshl_add_u64 v[10:11], s[4:5], 0, v[10:11]
	v_lshl_add_u64 v[10:11], v[10:11], 0, v[32:33]
	v_cmp_gt_u32_e32 vcc, 2, v24
	s_nop 1
	v_cndmask_b32_e32 v23, 0, v11, vcc
	v_cndmask_b32_e32 v22, 0, v10, vcc

.LBB0_411:
	s_or_b64 exec, exec, s[2:3]
	v_cmp_ne_u32_e32 vcc, 0, v24
	s_and_saveexec_b64 s[2:3], vcc
	s_xor_b64 s[2:3], exec, s[2:3]
	s_cbranch_execz .LBB0_413
	v_readlane_b32 s16, v248, 45
	v_lshlrev_b64 v[10:11], 12, v[30:31]
	v_readlane_b32 s17, v248, 46
	s_nop 1
	v_lshl_add_u64 v[10:11], s[16:17], 0, v[10:11]
	v_lshl_add_u64 v[10:11], v[10:11], 0, v[28:29]
	s_waitcnt vmcnt(0)
	v_mov_b32_e32 v12, v100
	v_mov_b32_e32 v13, v101
	v_mov_b32_e32 v14, v102
	v_mov_b32_e32 v15, v103
	v_lshlrev_b32_e32 v10, 16, v12
	v_and_b32_e32 v16, 0xffff0000, v12
	v_lshlrev_b32_e32 v11, 16, v13
	v_and_b32_e32 v17, 0xffff0000, v13
	v_lshlrev_b32_e32 v34, 16, v14
	v_and_b32_e32 v12, 0xffff0000, v14
	v_lshlrev_b32_e32 v35, 16, v15
	v_and_b32_e32 v13, 0xffff0000, v15

.LBB0_425:
	s_andn2_saveexec_b64 s[2:3], s[2:3]
	s_cbranch_execz .LBB0_406
	v_readlane_b32 s16, v248, 45
	v_lshlrev_b64 v[14:15], 12, v[30:31]
	v_readlane_b32 s17, v248, 46
	s_nop 1
	v_lshl_add_u64 v[14:15], s[16:17], 0, v[14:15]
	v_lshl_add_u64 v[14:15], v[14:15], 0, v[28:29]
	v_add_co_u32_e32 v14, vcc, 0xffffe000, v14
	s_nop 1
	v_addc_co_u32_e32 v15, vcc, -1, v15, vcc
	s_waitcnt vmcnt(0)
	v_mov_b32_e32 v18, v106
	v_mov_b32_e32 v19, v107
	v_mov_b32_e32 v20, v108
	v_mov_b32_e32 v21, v109
	v_lshlrev_b32_e32 v36, 16, v18
	v_and_b32_e32 v24, 0xffff0000, v18
	v_lshlrev_b32_e32 v37, 16, v19
	v_and_b32_e32 v25, 0xffff0000, v19
	v_lshlrev_b32_e32 v14, 16, v20
	v_and_b32_e32 v20, 0xffff0000, v20
	v_lshlrev_b32_e32 v15, 16, v21
	v_and_b32_e32 v21, 0xffff0000, v21
	s_branch .LBB0_406
